# combination: LRU x-gate MFMAs in the shadow of a-gate arithmetic, IN-phase weight tile touch-ahead, barrier polls without sleep
# baseline (speedup 1.0000x reference)
; __device__ __forceinline__ u16 f2bf(float x) { return (u16)(cvtpk(x, 0.f) & 0xffffu); }
; template <int PASS>
; __device__ __forceinline__ void lru_tile_phase(const Params& p, int jl, int Mrows, char* smem, int tid, int bid) {
;     ...
;     unsigned gv[16]; float carry_in = 0.f;
;     if (PASS == 2) {
;       const int ch = tid & 127, tg = tid >> 7;
; #pragma unroll
;       for (int i = 0; i < 16; ++i) gv[i] = P2[(size_t)(rowbase + tg * 16 + i) * 2048 + n * 128 + ch];
;       if (tid < 256) carry_in = carry[(size_t)(tt * 2 + (tid >> 7)) * 1024 + n * 128 + (tid & 127)];
;     }
;     {
;       const int ch = tid & 127, tg = tid >> 7, t0 = tg * 16;
;       const int col = n * 128 + ch;
;       float cw0 = p.in[18][(size_t)(jl * 4 + 0) * 1024 + col], cw1 = p.in[18][(size_t)(jl * 4 + 1) * 1024 + col];
;       float cw2 = p.in[18][(size_t)(jl * 4 + 2) * 1024 + col], cw3 = p.in[18][(size_t)(jl * 4 + 3) * 1024 + col];
;       const float cb = p.in[19][(size_t)jl * 1024 + col];
;       float xb[19]; unsigned xraw[19];
;       const u16* xsrc = P2 + (size_t)(rowbase - sloc) * 2048 + 1024 + col;
; #pragma unroll
;       for (int i = 0; i < 19; ++i) {
;         const int s = sloc + t0 + i - 2;
;         const int sc = s < 0 ? 0 : (s >= TT ? TT - 1 : s);
;         xraw[i] = xsrc[(size_t)sc * 2048];
;       }
; #pragma unroll
;       for (int i = 0; i < 19; ++i) {
;         const int s = sloc + t0 + i - 2;
;         xb[i] = (s >= 0 && s < TT) ? __uint_as_float(xraw[i] << 16) : 0.f;
;       }
; #pragma unroll
;       for (int i = 0; i < 16; ++i) {
;         const float xc = cb + cw0 * xb[i] + cw1 * xb[i + 1] + cw2 * xb[i + 2] + cw3 * xb[i + 3];
;         *(u16*)(xcL + swz256(t0 + i, ch >> 3) + (ch & 7) * 2) = f2bf(xc);
;       }
;     }
;     __syncthreads();
.Llru2_nloaded:
	s_movk_i32 s0, 0x1000
	s_cmp_lt_u32 s8, 512
	s_cselect_b32 s4, 0, 512
	s_cselect_b32 s5, 0, 0x8000
	s_cselect_b32 s1, 63, 3
	s_cselect_b32 s11, s0, 0x100
	s_sub_u32 s0, s8, s4
	s_lshl_b32 s9, s0, 6
	s_add_u32 s9, s9, s5
	s_and_b32 s10, s0, s1
	s_lshl_b32 s10, s10, 6
	s_cmp_eq_u32 s10, 0
	s_cselect_b32 s4, 0, -2
	s_add_u32 s0, s10, 64
	s_cmp_eq_u32 s0, s11
	s_cselect_b32 s5, 63, 0x41
	s_lshl_b32 s0, s9, 12
	s_lshl_b32 s1, s7, 8
	s_add_u32 s0, s0, s1
	s_add_u32 s20, s92, s0
	s_addc_u32 s21, s93, 0
	s_sub_u32 s0, s20, 0x1800
	s_subb_u32 s1, s21, 0
	global_load_dwordx4 v[92:95], v192, s[20:21]
	global_load_dwordx4 v[244:247], v192, s[20:21] offset:16
	s_lshl_b32 s0, s8, 11
	s_lshl_b32 s1, s7, 7
	s_add_u32 s0, s0, s1
	s_lshl_b32 s0, s0, 2
	s_add_u32 s0, s24, s0
	s_addc_u32 s1, s25, 0
	v_lshlrev_b32_e32 v196, 2, v194
	global_load_dword v252, v196, s[0:1]
	v_mov_b32_e32 v20, v132
	v_mov_b32_e32 v21, v133
	v_mov_b32_e32 v22, v134
	v_mov_b32_e32 v23, v135
	v_mov_b32_e32 v24, v136
	v_mov_b32_e32 v25, v137
	v_mov_b32_e32 v26, v138
	v_mov_b32_e32 v27, v139
	v_mov_b32_e32 v28, v132
	v_mov_b32_e32 v29, v133
	v_mov_b32_e32 v30, v134
	v_mov_b32_e32 v31, v135
	v_mov_b32_e32 v32, v136
	v_mov_b32_e32 v33, v137
	v_mov_b32_e32 v34, v138
	v_mov_b32_e32 v35, v139
	s_waitcnt vmcnt(9)
	v_cmp_eq_u32_e32 vcc, v44, v49
	s_nop 1
	v_cndmask_b32_e32 v56, 0, v56, vcc
	v_cndmask_b32_e32 v57, 0, v57, vcc
	v_cndmask_b32_e32 v58, 0, v58, vcc
	v_cndmask_b32_e32 v59, 0, v59, vcc
	v_lshlrev_b32_e32 v36, 16, v56
	v_and_b32_e32 v37, 0xffff0000, v56
	v_lshlrev_b32_e32 v38, 16, v57
	v_and_b32_e32 v39, 0xffff0000, v57
	v_lshlrev_b32_e32 v40, 16, v58
	v_and_b32_e32 v41, 0xffff0000, v58
	v_lshlrev_b32_e32 v42, 16, v59
	v_and_b32_e32 v43, 0xffff0000, v59
	v_fmac_f32_e32 v20, v100, v36
	v_fmac_f32_e32 v21, v101, v37
	v_fmac_f32_e32 v22, v102, v38
	v_fmac_f32_e32 v23, v103, v39
	v_fmac_f32_e32 v24, v104, v40
	v_fmac_f32_e32 v25, v105, v41
	v_fmac_f32_e32 v26, v106, v42
	v_fmac_f32_e32 v27, v107, v43
	s_waitcnt vmcnt(8)
	v_cmp_eq_u32_e32 vcc, v45, v50
	s_nop 1
	v_cndmask_b32_e32 v60, 0, v60, vcc
	v_cndmask_b32_e32 v61, 0, v61, vcc
	v_cndmask_b32_e32 v62, 0, v62, vcc
	v_cndmask_b32_e32 v63, 0, v63, vcc
	v_lshlrev_b32_e32 v36, 16, v60
	v_and_b32_e32 v37, 0xffff0000, v60
	v_lshlrev_b32_e32 v38, 16, v61
	v_and_b32_e32 v39, 0xffff0000, v61
	v_lshlrev_b32_e32 v40, 16, v62
	v_and_b32_e32 v41, 0xffff0000, v62
	v_lshlrev_b32_e32 v42, 16, v63
	v_and_b32_e32 v43, 0xffff0000, v63
	v_fmac_f32_e32 v20, v108, v36
	v_fmac_f32_e32 v21, v109, v37
	v_fmac_f32_e32 v22, v110, v38
	v_fmac_f32_e32 v23, v111, v39
	v_fmac_f32_e32 v24, v112, v40
	v_fmac_f32_e32 v25, v113, v41
	v_fmac_f32_e32 v26, v114, v42
	v_fmac_f32_e32 v27, v115, v43
	v_fmac_f32_e32 v28, v100, v36
	v_fmac_f32_e32 v29, v101, v37
	v_fmac_f32_e32 v30, v102, v38
	v_fmac_f32_e32 v31, v103, v39
	v_fmac_f32_e32 v32, v104, v40
	v_fmac_f32_e32 v33, v105, v41
	v_fmac_f32_e32 v34, v106, v42
	v_fmac_f32_e32 v35, v107, v43
	s_waitcnt vmcnt(7)
	v_cmp_eq_u32_e32 vcc, v46, v51
	s_nop 1
	v_cndmask_b32_e32 v64, 0, v64, vcc
	v_cndmask_b32_e32 v65, 0, v65, vcc
	v_cndmask_b32_e32 v66, 0, v66, vcc
	v_cndmask_b32_e32 v67, 0, v67, vcc
	v_lshlrev_b32_e32 v36, 16, v64
	v_and_b32_e32 v37, 0xffff0000, v64
	v_lshlrev_b32_e32 v38, 16, v65
	v_and_b32_e32 v39, 0xffff0000, v65
	v_lshlrev_b32_e32 v40, 16, v66
	v_and_b32_e32 v41, 0xffff0000, v66
	v_lshlrev_b32_e32 v42, 16, v67
	v_and_b32_e32 v43, 0xffff0000, v67
	v_fmac_f32_e32 v20, v116, v36
	v_fmac_f32_e32 v21, v117, v37
	v_fmac_f32_e32 v22, v118, v38
	v_fmac_f32_e32 v23, v119, v39
	v_fmac_f32_e32 v24, v120, v40
	v_fmac_f32_e32 v25, v121, v41
	v_fmac_f32_e32 v26, v122, v42
	v_fmac_f32_e32 v27, v123, v43
	v_fmac_f32_e32 v28, v108, v36
	v_fmac_f32_e32 v29, v109, v37
	v_fmac_f32_e32 v30, v110, v38
	v_fmac_f32_e32 v31, v111, v39
	v_fmac_f32_e32 v32, v112, v40
	v_fmac_f32_e32 v33, v113, v41
	v_fmac_f32_e32 v34, v114, v42
	v_fmac_f32_e32 v35, v115, v43
	s_waitcnt vmcnt(6)
	v_cmp_eq_u32_e32 vcc, v47, v52
	s_nop 1
	v_cndmask_b32_e32 v68, 0, v68, vcc
	v_cndmask_b32_e32 v69, 0, v69, vcc
	v_cndmask_b32_e32 v70, 0, v70, vcc
	v_cndmask_b32_e32 v71, 0, v71, vcc
	v_lshlrev_b32_e32 v36, 16, v68
	v_and_b32_e32 v37, 0xffff0000, v68
	v_lshlrev_b32_e32 v38, 16, v69
	v_and_b32_e32 v39, 0xffff0000, v69
	v_lshlrev_b32_e32 v40, 16, v70
	v_and_b32_e32 v41, 0xffff0000, v70
	v_lshlrev_b32_e32 v42, 16, v71
	v_and_b32_e32 v43, 0xffff0000, v71
	v_fmac_f32_e32 v20, v124, v36
	v_fmac_f32_e32 v21, v125, v37
	v_fmac_f32_e32 v22, v126, v38
	v_fmac_f32_e32 v23, v127, v39
	v_fmac_f32_e32 v24, v128, v40
	v_fmac_f32_e32 v25, v129, v41
	v_fmac_f32_e32 v26, v130, v42
	v_fmac_f32_e32 v27, v131, v43
	v_fmac_f32_e32 v28, v116, v36
	v_fmac_f32_e32 v29, v117, v37
	v_fmac_f32_e32 v30, v118, v38
	v_fmac_f32_e32 v31, v119, v39
	v_fmac_f32_e32 v32, v120, v40
	v_fmac_f32_e32 v33, v121, v41
	v_fmac_f32_e32 v34, v122, v42
	v_fmac_f32_e32 v35, v123, v43
	s_waitcnt vmcnt(5)
	v_cmp_eq_u32_e32 vcc, v48, v53
	s_nop 1
	v_cndmask_b32_e32 v72, 0, v72, vcc
	v_cndmask_b32_e32 v73, 0, v73, vcc
	v_cndmask_b32_e32 v74, 0, v74, vcc
	v_cndmask_b32_e32 v75, 0, v75, vcc
	v_lshlrev_b32_e32 v36, 16, v72
	v_and_b32_e32 v37, 0xffff0000, v72
	v_lshlrev_b32_e32 v38, 16, v73
	v_and_b32_e32 v39, 0xffff0000, v73
	v_lshlrev_b32_e32 v40, 16, v74
	v_and_b32_e32 v41, 0xffff0000, v74
	v_lshlrev_b32_e32 v42, 16, v75
	v_and_b32_e32 v43, 0xffff0000, v75
	v_fmac_f32_e32 v28, v124, v36
	v_fmac_f32_e32 v29, v125, v37
	v_fmac_f32_e32 v30, v126, v38
	v_fmac_f32_e32 v31, v127, v39
	v_fmac_f32_e32 v32, v128, v40
	v_fmac_f32_e32 v33, v129, v41
	v_fmac_f32_e32 v34, v130, v42
	v_fmac_f32_e32 v35, v131, v43
	v_cvt_pk_bf16_f32 v36, v20, v21
	v_cvt_pk_bf16_f32 v37, v22, v23
	v_cvt_pk_bf16_f32 v38, v24, v25
	v_cvt_pk_bf16_f32 v39, v26, v27
	v_cvt_pk_bf16_f32 v40, v28, v29
	v_cvt_pk_bf16_f32 v41, v30, v31
	v_cvt_pk_bf16_f32 v42, v32, v33
	v_cvt_pk_bf16_f32 v43, v34, v35
	ds_write_b128 v183, v[36:39]
	ds_write_b128 v184, v[40:43]
	s_waitcnt lgkmcnt(0)
	s_barrier
; template <int PASS>
; __device__ __forceinline__ void lru_tile_phase(const Params& p, int jl, int Mrows, char* smem, int tid, int bid) {
;     ...
;       for (int tb = 0; tb < 2; ++tb) {
;         f32x16 acc0, acc1;
; #pragma unroll
;         for (int r = 0; r < 16; ++r) { acc0[r] = 0.f; acc1[r] = 0.f; }
;         bf16x8 af[8];
; #pragma unroll
;         for (int k16 = 0; k16 < 8; ++k16) af[k16] = *(const bf16x8*)(xcL + swz256(tb * 32 + l32, k16 * 2 + hi));
; #pragma unroll
;         for (int k16 = 0; k16 < 8; ++k16) {
;           acc0 = __builtin_amdgcn_mfma_f32_32x32x16_bf16(af[k16], wb0[k16], acc0, 0, 0, 0);
;           acc1 = __builtin_amdgcn_mfma_f32_32x32x16_bf16(af[k16], wb1[k16], acc1, 0, 0, 0);
;         }
	ds_read_b128 v[48:51], v185 offset:0
	v_xor_b32_e32 v196, 32, v185
	ds_read_b128 v[52:55], v196 offset:0
	v_xor_b32_e32 v195, 64, v185
	ds_read_b128 v[56:59], v195 offset:0
	v_xor_b32_e32 v196, 96, v185
	ds_read_b128 v[60:63], v196 offset:0
	v_xor_b32_e32 v195, 128, v185
	ds_read_b128 v[64:67], v195 offset:0
	v_xor_b32_e32 v196, 160, v185
	ds_read_b128 v[68:71], v196 offset:0
	v_xor_b32_e32 v195, 192, v185
	ds_read_b128 v[72:75], v195 offset:0
	v_xor_b32_e32 v196, 224, v185
	ds_read_b128 v[76:79], v196 offset:0
	s_waitcnt lgkmcnt(7)
	v_mfma_f32_32x32x16_bf16 v[0:15], v[48:51], v[140:143], 0
	s_waitcnt lgkmcnt(6)
	v_mfma_f32_32x32x16_bf16 v[0:15], v[52:55], v[144:147], v[0:15]
	s_waitcnt lgkmcnt(5)
	v_mfma_f32_32x32x16_bf16 v[0:15], v[56:59], v[148:151], v[0:15]
	s_waitcnt lgkmcnt(4)
	v_mfma_f32_32x32x16_bf16 v[0:15], v[60:63], v[152:155], v[0:15]
	s_waitcnt lgkmcnt(3)
	v_mfma_f32_32x32x16_bf16 v[0:15], v[64:67], v[156:159], v[0:15]
	s_waitcnt lgkmcnt(2)
	v_mfma_f32_32x32x16_bf16 v[0:15], v[68:71], v[160:163], v[0:15]
	s_waitcnt lgkmcnt(1)
	v_mfma_f32_32x32x16_bf16 v[0:15], v[72:75], v[164:167], v[0:15]
	s_waitcnt lgkmcnt(0)
	v_mfma_f32_32x32x16_bf16 v[0:15], v[76:79], v[168:171], v[0:15]
	s_and_b32 s0, s27, 3
	s_cmp_eq_u32 s0, 0
	s_cbranch_scc0 .Llru2_id0_0
	v_mfma_f32_32x32x16_bf16 v[32:47], v[48:51], v[172:175], 0
	v_mfma_f32_32x32x16_bf16 v[32:47], v[52:55], v[176:179], v[32:47]

; __device__ __forceinline__ float bf2f(u16 x) { return __uint_as_float(((unsigned)x) << 16); }
; __device__ __forceinline__ float fexp(float x) { return __builtin_amdgcn_exp2f(x * 1.4426950408889634f); }
; __device__ __forceinline__ int crow(int r, int hi) { return (r & 3) + 8 * (r >> 2) + 4 * hi; }
; template <int PASS>
; __device__ __forceinline__ void lru_tile_phase(const Params& p, int jl, int Mrows, char* smem, int tid, int bid) {
;     ...
;         for (int k16 = 0; k16 < 8; ++k16) {
;           acc0 = __builtin_amdgcn_mfma_f32_32x32x16_bf16(af[k16], wb0[k16], acc0, 0, 0, 0);
;           acc1 = __builtin_amdgcn_mfma_f32_32x32x16_bf16(af[k16], wb1[k16], acc1, 0, 0, 0);
;         }
; #pragma unroll
;         for (int r = 0; r < 16; ++r) {
;           const int tok = tb * 32 + crow(r, hi);
;           const float xc = bf2f(*(const u16*)(xcL + swz256(tok, chl >> 3) + (chl & 7) * 2));
;           const float la = c_sp * __builtin_amdgcn_rcpf(1.f + fexp(-(acc0[r] + c_ba)));
;           const float ii = __builtin_amdgcn_rcpf(1.f + fexp(-(acc1[r] + c_bx)));
;           const float av = fexp(la);
;           aL[(dh * 64 + tok) * 128 + chl] = av;
;           uL[(dh * 64 + tok) * 128 + chl] = __builtin_amdgcn_sqrtf(fmaxf(1.f - av * av, 0.f)) * (ii * xc);
.Llru2_id0_3:
	v_mfma_f32_32x32x16_bf16 v[16:31], v[48:51], v[204:207], 0
	v_fma_f32 v80, v0, v91, v180
	v_fma_f32 v88, v1, v91, v180
	v_exp_f32_e32 v80, v80
	v_exp_f32_e32 v88, v88
	v_add_f32_e32 v80, 1.0, v80
	v_add_f32_e32 v88, 1.0, v88
	v_rcp_f32_e32 v80, v80
	v_rcp_f32_e32 v88, v88
	v_mul_f32_e32 v80, v182, v80
	v_mul_f32_e32 v88, v182, v88
	v_exp_f32_e32 v80, v80
	v_exp_f32_e32 v88, v88
	v_fma_f32 v0, -v80, v80, 1.0
	v_fma_f32 v1, -v88, v88, 1.0
	v_max_f32_e32 v0, 0, v0
	v_max_f32_e32 v1, 0, v1
	v_sqrt_f32_e32 v0, v0
	v_sqrt_f32_e32 v1, v1
	ds_write_b32 v186, v80 offset:0
	ds_write_b32 v186, v88 offset:512
	v_mfma_f32_32x32x16_bf16 v[16:31], v[52:55], v[208:211], v[16:31]
	v_fma_f32 v80, v2, v91, v180
	v_fma_f32 v88, v3, v91, v180
	v_exp_f32_e32 v80, v80
	v_exp_f32_e32 v88, v88
	v_add_f32_e32 v80, 1.0, v80
	v_add_f32_e32 v88, 1.0, v88
	v_rcp_f32_e32 v80, v80
	v_rcp_f32_e32 v88, v88
	v_mul_f32_e32 v80, v182, v80
	v_mul_f32_e32 v88, v182, v88
	v_exp_f32_e32 v80, v80
	v_exp_f32_e32 v88, v88
	v_fma_f32 v2, -v80, v80, 1.0
	v_fma_f32 v3, -v88, v88, 1.0
	v_max_f32_e32 v2, 0, v2
	v_max_f32_e32 v3, 0, v3
	v_sqrt_f32_e32 v2, v2
	v_sqrt_f32_e32 v3, v3
	ds_write_b32 v186, v80 offset:1024
	ds_write_b32 v186, v88 offset:1536
	v_mfma_f32_32x32x16_bf16 v[16:31], v[56:59], v[212:215], v[16:31]
	v_fma_f32 v80, v4, v91, v180
	v_fma_f32 v88, v5, v91, v180
	v_exp_f32_e32 v80, v80
	v_exp_f32_e32 v88, v88
	v_add_f32_e32 v80, 1.0, v80
	v_add_f32_e32 v88, 1.0, v88
	v_rcp_f32_e32 v80, v80
	v_rcp_f32_e32 v88, v88
	v_mul_f32_e32 v80, v182, v80
	v_mul_f32_e32 v88, v182, v88
	v_exp_f32_e32 v80, v80
	v_exp_f32_e32 v88, v88
	v_fma_f32 v4, -v80, v80, 1.0
	v_fma_f32 v5, -v88, v88, 1.0
	v_max_f32_e32 v4, 0, v4
	v_max_f32_e32 v5, 0, v5
	v_sqrt_f32_e32 v4, v4
	v_sqrt_f32_e32 v5, v5
	ds_write_b32 v186, v80 offset:4096
	ds_write_b32 v186, v88 offset:4608
	v_mfma_f32_32x32x16_bf16 v[16:31], v[60:63], v[216:219], v[16:31]
	v_fma_f32 v80, v6, v91, v180
	v_fma_f32 v88, v7, v91, v180
	v_exp_f32_e32 v80, v80
	v_exp_f32_e32 v88, v88
	v_add_f32_e32 v80, 1.0, v80
	v_add_f32_e32 v88, 1.0, v88
	v_rcp_f32_e32 v80, v80
	v_rcp_f32_e32 v88, v88
	v_mul_f32_e32 v80, v182, v80
	v_mul_f32_e32 v88, v182, v88
	v_exp_f32_e32 v80, v80
	v_exp_f32_e32 v88, v88
	v_fma_f32 v6, -v80, v80, 1.0
	v_fma_f32 v7, -v88, v88, 1.0
	v_max_f32_e32 v6, 0, v6
	v_max_f32_e32 v7, 0, v7
	v_sqrt_f32_e32 v6, v6
	v_sqrt_f32_e32 v7, v7
	ds_write_b32 v186, v80 offset:5120
	ds_write_b32 v186, v88 offset:5632
	v_mfma_f32_32x32x16_bf16 v[16:31], v[64:67], v[220:223], v[16:31]
	v_fma_f32 v80, v8, v91, v180
	v_fma_f32 v88, v9, v91, v180
	v_exp_f32_e32 v80, v80
	v_exp_f32_e32 v88, v88
	v_add_f32_e32 v80, 1.0, v80
	v_add_f32_e32 v88, 1.0, v88
	v_rcp_f32_e32 v80, v80
	v_rcp_f32_e32 v88, v88
	v_mul_f32_e32 v80, v182, v80
	v_mul_f32_e32 v88, v182, v88
	v_exp_f32_e32 v80, v80
	v_exp_f32_e32 v88, v88
	v_fma_f32 v8, -v80, v80, 1.0
	v_fma_f32 v9, -v88, v88, 1.0
	v_max_f32_e32 v8, 0, v8
	v_max_f32_e32 v9, 0, v9
	v_sqrt_f32_e32 v8, v8
	v_sqrt_f32_e32 v9, v9
	ds_write_b32 v186, v80 offset:8192
	ds_write_b32 v186, v88 offset:8704
	v_mfma_f32_32x32x16_bf16 v[16:31], v[68:71], v[224:227], v[16:31]
	v_fma_f32 v80, v10, v91, v180
	v_fma_f32 v88, v11, v91, v180
	v_exp_f32_e32 v80, v80
	v_exp_f32_e32 v88, v88
	v_add_f32_e32 v80, 1.0, v80
	v_add_f32_e32 v88, 1.0, v88
	v_rcp_f32_e32 v80, v80
	v_rcp_f32_e32 v88, v88
	v_mul_f32_e32 v80, v182, v80
	v_mul_f32_e32 v88, v182, v88
	v_exp_f32_e32 v80, v80
	v_exp_f32_e32 v88, v88
	v_fma_f32 v10, -v80, v80, 1.0
	v_fma_f32 v11, -v88, v88, 1.0
	v_max_f32_e32 v10, 0, v10
	v_max_f32_e32 v11, 0, v11
	v_sqrt_f32_e32 v10, v10
	v_sqrt_f32_e32 v11, v11
	ds_write_b32 v186, v80 offset:9216
	ds_write_b32 v186, v88 offset:9728
	v_mfma_f32_32x32x16_bf16 v[16:31], v[72:75], v[228:231], v[16:31]
	v_fma_f32 v80, v12, v91, v180
	v_fma_f32 v88, v13, v91, v180
	v_exp_f32_e32 v80, v80
	v_exp_f32_e32 v88, v88
	v_add_f32_e32 v80, 1.0, v80
	v_add_f32_e32 v88, 1.0, v88
	v_rcp_f32_e32 v80, v80
	v_rcp_f32_e32 v88, v88
	v_mul_f32_e32 v80, v182, v80
	v_mul_f32_e32 v88, v182, v88
	v_exp_f32_e32 v80, v80
	v_exp_f32_e32 v88, v88
	v_fma_f32 v12, -v80, v80, 1.0
	v_fma_f32 v13, -v88, v88, 1.0
	v_max_f32_e32 v12, 0, v12
	v_max_f32_e32 v13, 0, v13
	v_sqrt_f32_e32 v12, v12
	v_sqrt_f32_e32 v13, v13
	ds_write_b32 v186, v80 offset:12288
	ds_write_b32 v186, v88 offset:12800
	v_mfma_f32_32x32x16_bf16 v[16:31], v[76:79], v[232:235], v[16:31]
	v_fma_f32 v80, v14, v91, v180
	v_fma_f32 v88, v15, v91, v180
	v_exp_f32_e32 v80, v80
	v_exp_f32_e32 v88, v88
	v_add_f32_e32 v80, 1.0, v80
	v_add_f32_e32 v88, 1.0, v88
	v_rcp_f32_e32 v80, v80
	v_rcp_f32_e32 v88, v88
	v_mul_f32_e32 v80, v182, v80
	v_mul_f32_e32 v88, v182, v88
	v_exp_f32_e32 v80, v80
	v_exp_f32_e32 v88, v88
; __device__ __forceinline__ float bf2f(u16 x) { return __uint_as_float(((unsigned)x) << 16); }
; __device__ __forceinline__ float fexp(float x) { return __builtin_amdgcn_exp2f(x * 1.4426950408889634f); }
; __device__ __forceinline__ int crow(int r, int hi) { return (r & 3) + 8 * (r >> 2) + 4 * hi; }
; template <int PASS>
; __device__ __forceinline__ void lru_tile_phase(const Params& p, int jl, int Mrows, char* smem, int tid, int bid) {
;     ...
;         bf16x8 af[8];
; #pragma unroll
;         for (int k16 = 0; k16 < 8; ++k16) af[k16] = *(const bf16x8*)(xcL + swz256(tb * 32 + l32, k16 * 2 + hi));
; #pragma unroll
;         for (int k16 = 0; k16 < 8; ++k16) {
;           acc0 = __builtin_amdgcn_mfma_f32_32x32x16_bf16(af[k16], wb0[k16], acc0, 0, 0, 0);
;           acc1 = __builtin_amdgcn_mfma_f32_32x32x16_bf16(af[k16], wb1[k16], acc1, 0, 0, 0);
;     ...
; #pragma unroll
;         for (int r = 0; r < 16; ++r) {
;           const int tok = tb * 32 + crow(r, hi);
;           const float xc = bf2f(*(const u16*)(xcL + swz256(tok, chl >> 3) + (chl & 7) * 2));
;           const float la = c_sp * __builtin_amdgcn_rcpf(1.f + fexp(-(acc0[r] + c_ba)));
;           const float ii = __builtin_amdgcn_rcpf(1.f + fexp(-(acc1[r] + c_bx)));
;           const float av = fexp(la);
;           aL[(dh * 64 + tok) * 128 + chl] = av;
;           uL[(dh * 64 + tok) * 128 + chl] = __builtin_amdgcn_sqrtf(fmaxf(1.f - av * av, 0.f)) * (ii * xc);
	v_fma_f32 v14, -v80, v80, 1.0
	v_fma_f32 v15, -v88, v88, 1.0
	v_max_f32_e32 v14, 0, v14
	v_max_f32_e32 v15, 0, v15
	v_sqrt_f32_e32 v14, v14
	v_sqrt_f32_e32 v15, v15
	ds_write_b32 v186, v80 offset:13312
	ds_write_b32 v186, v88 offset:13824
	ds_read_b128 v[48:51], v185 offset:8192
	v_xor_b32_e32 v196, 32, v185
	ds_read_b128 v[52:55], v196 offset:8192
	v_xor_b32_e32 v195, 64, v185
	ds_read_b128 v[56:59], v195 offset:8192
	v_xor_b32_e32 v196, 96, v185
	ds_read_b128 v[60:63], v196 offset:8192
	v_xor_b32_e32 v195, 128, v185
	ds_read_b128 v[64:67], v195 offset:8192
	v_xor_b32_e32 v196, 160, v185
	ds_read_b128 v[68:71], v196 offset:8192
	v_xor_b32_e32 v195, 192, v185
	ds_read_b128 v[72:75], v195 offset:8192
	v_xor_b32_e32 v196, 224, v185
	ds_read_b128 v[76:79], v196 offset:8192
	v_fma_f32 v81, v16, v91, v181
	v_fma_f32 v89, v17, v91, v181
	v_exp_f32_e32 v81, v81
	v_exp_f32_e32 v89, v89
	v_add_f32_e32 v81, 1.0, v81
	v_add_f32_e32 v89, 1.0, v89
	v_rcp_f32_e32 v81, v81
	v_rcp_f32_e32 v89, v89
	v_mul_f32_e32 v81, v81, v32
	v_mul_f32_e32 v89, v89, v33
	v_mul_f32_e32 v81, v0, v81
	v_mul_f32_e32 v89, v1, v89
	ds_write_b32 v187, v81 offset:0
	ds_write_b32 v187, v89 offset:512
	v_fma_f32 v81, v18, v91, v181
	v_fma_f32 v89, v19, v91, v181
	v_exp_f32_e32 v81, v81
	v_exp_f32_e32 v89, v89
	v_add_f32_e32 v81, 1.0, v81
	v_add_f32_e32 v89, 1.0, v89
	v_rcp_f32_e32 v81, v81
	v_rcp_f32_e32 v89, v89
	v_mul_f32_e32 v81, v81, v34
	v_mul_f32_e32 v89, v89, v35
	v_mul_f32_e32 v81, v2, v81
	v_mul_f32_e32 v89, v3, v89
	ds_write_b32 v187, v81 offset:1024
	ds_write_b32 v187, v89 offset:1536
	v_fma_f32 v81, v20, v91, v181
	v_fma_f32 v89, v21, v91, v181
	v_exp_f32_e32 v81, v81
	v_exp_f32_e32 v89, v89
	v_add_f32_e32 v81, 1.0, v81
	v_add_f32_e32 v89, 1.0, v89
	v_rcp_f32_e32 v81, v81
	v_rcp_f32_e32 v89, v89
	v_mul_f32_e32 v81, v81, v36
	v_mul_f32_e32 v89, v89, v37
	v_mul_f32_e32 v81, v4, v81
	v_mul_f32_e32 v89, v5, v89
	ds_write_b32 v187, v81 offset:4096
	ds_write_b32 v187, v89 offset:4608
	v_fma_f32 v81, v22, v91, v181
	v_fma_f32 v89, v23, v91, v181
	v_exp_f32_e32 v81, v81
	v_exp_f32_e32 v89, v89
	v_add_f32_e32 v81, 1.0, v81
	v_add_f32_e32 v89, 1.0, v89
	v_rcp_f32_e32 v81, v81
	v_rcp_f32_e32 v89, v89
	v_mul_f32_e32 v81, v81, v38
	v_mul_f32_e32 v89, v89, v39
	v_mul_f32_e32 v81, v6, v81
	v_mul_f32_e32 v89, v7, v89
	ds_write_b32 v187, v81 offset:5120
	ds_write_b32 v187, v89 offset:5632
	v_fma_f32 v81, v24, v91, v181
	v_fma_f32 v89, v25, v91, v181
	v_exp_f32_e32 v81, v81
	v_exp_f32_e32 v89, v89
	v_add_f32_e32 v81, 1.0, v81
	v_add_f32_e32 v89, 1.0, v89
	v_rcp_f32_e32 v81, v81
	v_rcp_f32_e32 v89, v89
	v_mul_f32_e32 v81, v81, v40
	v_mul_f32_e32 v89, v89, v41
	v_mul_f32_e32 v81, v8, v81
	v_mul_f32_e32 v89, v9, v89
	ds_write_b32 v187, v81 offset:8192
	ds_write_b32 v187, v89 offset:8704
	v_fma_f32 v81, v26, v91, v181
	v_fma_f32 v89, v27, v91, v181
	v_exp_f32_e32 v81, v81
	v_exp_f32_e32 v89, v89
	v_add_f32_e32 v81, 1.0, v81
	v_add_f32_e32 v89, 1.0, v89
	v_rcp_f32_e32 v81, v81
	v_rcp_f32_e32 v89, v89
	v_mul_f32_e32 v81, v81, v42
	v_mul_f32_e32 v89, v89, v43
	v_mul_f32_e32 v81, v10, v81
	v_mul_f32_e32 v89, v11, v89
	ds_write_b32 v187, v81 offset:9216
	ds_write_b32 v187, v89 offset:9728
	v_fma_f32 v81, v28, v91, v181
	v_fma_f32 v89, v29, v91, v181
	v_exp_f32_e32 v81, v81
	v_exp_f32_e32 v89, v89
	v_add_f32_e32 v81, 1.0, v81
	v_add_f32_e32 v89, 1.0, v89
	v_rcp_f32_e32 v81, v81
	v_rcp_f32_e32 v89, v89
	v_mul_f32_e32 v81, v81, v44
	v_mul_f32_e32 v89, v89, v45
	v_mul_f32_e32 v81, v12, v81
	v_mul_f32_e32 v89, v13, v89
	ds_write_b32 v187, v81 offset:12288
	ds_write_b32 v187, v89 offset:12800
	v_fma_f32 v81, v30, v91, v181
	v_fma_f32 v89, v31, v91, v181
	v_exp_f32_e32 v81, v81
	v_exp_f32_e32 v89, v89
	v_add_f32_e32 v81, 1.0, v81
	v_add_f32_e32 v89, 1.0, v89
	v_rcp_f32_e32 v81, v81
	v_rcp_f32_e32 v89, v89
	v_mul_f32_e32 v81, v81, v46
	v_mul_f32_e32 v89, v89, v47
	v_mul_f32_e32 v81, v14, v81
	v_mul_f32_e32 v89, v15, v89
	ds_write_b32 v187, v81 offset:13312
	ds_write_b32 v187, v89 offset:13824
	s_waitcnt lgkmcnt(0)
	v_mfma_f32_32x32x16_bf16 v[0:15], v[48:51], v[140:143], 0
	v_mfma_f32_32x32x16_bf16 v[0:15], v[52:55], v[144:147], v[0:15]
	v_mfma_f32_32x32x16_bf16 v[0:15], v[56:59], v[148:151], v[0:15]
	v_mfma_f32_32x32x16_bf16 v[0:15], v[60:63], v[152:155], v[0:15]
	v_mfma_f32_32x32x16_bf16 v[0:15], v[64:67], v[156:159], v[0:15]
	v_mfma_f32_32x32x16_bf16 v[0:15], v[68:71], v[160:163], v[0:15]
	v_mfma_f32_32x32x16_bf16 v[0:15], v[72:75], v[164:167], v[0:15]
	v_mfma_f32_32x32x16_bf16 v[0:15], v[76:79], v[168:171], v[0:15]
	s_and_b32 s0, s27, 3
	s_cmp_eq_u32 s0, 0
	s_cbranch_scc0 .Llru2_id1_0
	v_mfma_f32_32x32x16_bf16 v[32:47], v[48:51], v[172:175], 0
	v_mfma_f32_32x32x16_bf16 v[32:47], v[52:55], v[176:179], v[32:47]

; __device__ __forceinline__ float bf2f(u16 x) { return __uint_as_float(((unsigned)x) << 16); }
; __device__ __forceinline__ float fexp(float x) { return __builtin_amdgcn_exp2f(x * 1.4426950408889634f); }
; __device__ __forceinline__ int crow(int r, int hi) { return (r & 3) + 8 * (r >> 2) + 4 * hi; }
; template <int PASS>
; __device__ __forceinline__ void lru_tile_phase(const Params& p, int jl, int Mrows, char* smem, int tid, int bid) {
;     ...
;         for (int k16 = 0; k16 < 8; ++k16) {
;           acc0 = __builtin_amdgcn_mfma_f32_32x32x16_bf16(af[k16], wb0[k16], acc0, 0, 0, 0);
;           acc1 = __builtin_amdgcn_mfma_f32_32x32x16_bf16(af[k16], wb1[k16], acc1, 0, 0, 0);
;         }
; #pragma unroll
;         for (int r = 0; r < 16; ++r) {
;           const int tok = tb * 32 + crow(r, hi);
;           const float xc = bf2f(*(const u16*)(xcL + swz256(tok, chl >> 3) + (chl & 7) * 2));
;           const float la = c_sp * __builtin_amdgcn_rcpf(1.f + fexp(-(acc0[r] + c_ba)));
;           const float ii = __builtin_amdgcn_rcpf(1.f + fexp(-(acc1[r] + c_bx)));
;           const float av = fexp(la);
;           aL[(dh * 64 + tok) * 128 + chl] = av;
;           uL[(dh * 64 + tok) * 128 + chl] = __builtin_amdgcn_sqrtf(fmaxf(1.f - av * av, 0.f)) * (ii * xc);
.Llru2_id1_3:
	v_mfma_f32_32x32x16_bf16 v[16:31], v[48:51], v[204:207], 0
	v_fma_f32 v80, v0, v91, v180
	v_fma_f32 v88, v1, v91, v180
	v_exp_f32_e32 v80, v80
	v_exp_f32_e32 v88, v88
	v_add_f32_e32 v80, 1.0, v80
	v_add_f32_e32 v88, 1.0, v88
	v_rcp_f32_e32 v80, v80
	v_rcp_f32_e32 v88, v88
	v_mul_f32_e32 v80, v182, v80
	v_mul_f32_e32 v88, v182, v88
	v_exp_f32_e32 v80, v80
	v_exp_f32_e32 v88, v88
	v_fma_f32 v0, -v80, v80, 1.0
	v_fma_f32 v1, -v88, v88, 1.0
	v_max_f32_e32 v0, 0, v0
	v_max_f32_e32 v1, 0, v1
	v_sqrt_f32_e32 v0, v0
	v_sqrt_f32_e32 v1, v1
	ds_write_b32 v186, v80 offset:16384
	ds_write_b32 v186, v88 offset:16896
	v_mfma_f32_32x32x16_bf16 v[16:31], v[52:55], v[208:211], v[16:31]
	v_fma_f32 v80, v2, v91, v180
	v_fma_f32 v88, v3, v91, v180
	v_exp_f32_e32 v80, v80
	v_exp_f32_e32 v88, v88
	v_add_f32_e32 v80, 1.0, v80
	v_add_f32_e32 v88, 1.0, v88
	v_rcp_f32_e32 v80, v80
	v_rcp_f32_e32 v88, v88
	v_mul_f32_e32 v80, v182, v80
	v_mul_f32_e32 v88, v182, v88
	v_exp_f32_e32 v80, v80
	v_exp_f32_e32 v88, v88
	v_fma_f32 v2, -v80, v80, 1.0
	v_fma_f32 v3, -v88, v88, 1.0
	v_max_f32_e32 v2, 0, v2
	v_max_f32_e32 v3, 0, v3
	v_sqrt_f32_e32 v2, v2
	v_sqrt_f32_e32 v3, v3
	ds_write_b32 v186, v80 offset:17408
	ds_write_b32 v186, v88 offset:17920
	v_mfma_f32_32x32x16_bf16 v[16:31], v[56:59], v[212:215], v[16:31]
	v_fma_f32 v80, v4, v91, v180
	v_fma_f32 v88, v5, v91, v180
	v_exp_f32_e32 v80, v80
	v_exp_f32_e32 v88, v88
	v_add_f32_e32 v80, 1.0, v80
	v_add_f32_e32 v88, 1.0, v88
	v_rcp_f32_e32 v80, v80
	v_rcp_f32_e32 v88, v88
	v_mul_f32_e32 v80, v182, v80
	v_mul_f32_e32 v88, v182, v88
	v_exp_f32_e32 v80, v80
	v_exp_f32_e32 v88, v88
	v_fma_f32 v4, -v80, v80, 1.0
	v_fma_f32 v5, -v88, v88, 1.0
	v_max_f32_e32 v4, 0, v4
	v_max_f32_e32 v5, 0, v5
	v_sqrt_f32_e32 v4, v4
	v_sqrt_f32_e32 v5, v5
	ds_write_b32 v186, v80 offset:20480
	ds_write_b32 v186, v88 offset:20992
	v_mfma_f32_32x32x16_bf16 v[16:31], v[60:63], v[216:219], v[16:31]
	v_fma_f32 v80, v6, v91, v180
	v_fma_f32 v88, v7, v91, v180
	v_exp_f32_e32 v80, v80
	v_exp_f32_e32 v88, v88
	v_add_f32_e32 v80, 1.0, v80
	v_add_f32_e32 v88, 1.0, v88
	v_rcp_f32_e32 v80, v80
	v_rcp_f32_e32 v88, v88
	v_mul_f32_e32 v80, v182, v80
	v_mul_f32_e32 v88, v182, v88
	v_exp_f32_e32 v80, v80
	v_exp_f32_e32 v88, v88
	v_fma_f32 v6, -v80, v80, 1.0
	v_fma_f32 v7, -v88, v88, 1.0
	v_max_f32_e32 v6, 0, v6
	v_max_f32_e32 v7, 0, v7
	v_sqrt_f32_e32 v6, v6
	v_sqrt_f32_e32 v7, v7
	ds_write_b32 v186, v80 offset:21504
	ds_write_b32 v186, v88 offset:22016
	v_mfma_f32_32x32x16_bf16 v[16:31], v[64:67], v[220:223], v[16:31]
	v_fma_f32 v80, v8, v91, v180
	v_fma_f32 v88, v9, v91, v180
	v_exp_f32_e32 v80, v80
	v_exp_f32_e32 v88, v88
	v_add_f32_e32 v80, 1.0, v80
	v_add_f32_e32 v88, 1.0, v88
	v_rcp_f32_e32 v80, v80
	v_rcp_f32_e32 v88, v88
	v_mul_f32_e32 v80, v182, v80
	v_mul_f32_e32 v88, v182, v88
	v_exp_f32_e32 v80, v80
	v_exp_f32_e32 v88, v88
	v_fma_f32 v8, -v80, v80, 1.0
	v_fma_f32 v9, -v88, v88, 1.0
	v_max_f32_e32 v8, 0, v8
	v_max_f32_e32 v9, 0, v9
	v_sqrt_f32_e32 v8, v8
	v_sqrt_f32_e32 v9, v9
	ds_write_b32 v186, v80 offset:24576
	ds_write_b32 v186, v88 offset:25088
	v_mfma_f32_32x32x16_bf16 v[16:31], v[68:71], v[224:227], v[16:31]
	v_fma_f32 v80, v10, v91, v180
	v_fma_f32 v88, v11, v91, v180
	v_exp_f32_e32 v80, v80
	v_exp_f32_e32 v88, v88
	v_add_f32_e32 v80, 1.0, v80
	v_add_f32_e32 v88, 1.0, v88
	v_rcp_f32_e32 v80, v80
	v_rcp_f32_e32 v88, v88
	v_mul_f32_e32 v80, v182, v80
	v_mul_f32_e32 v88, v182, v88
	v_exp_f32_e32 v80, v80
	v_exp_f32_e32 v88, v88
	v_fma_f32 v10, -v80, v80, 1.0
	v_fma_f32 v11, -v88, v88, 1.0
	v_max_f32_e32 v10, 0, v10
	v_max_f32_e32 v11, 0, v11
	v_sqrt_f32_e32 v10, v10
	v_sqrt_f32_e32 v11, v11
	ds_write_b32 v186, v80 offset:25600
	ds_write_b32 v186, v88 offset:26112
	v_mfma_f32_32x32x16_bf16 v[16:31], v[72:75], v[228:231], v[16:31]
	v_fma_f32 v80, v12, v91, v180
	v_fma_f32 v88, v13, v91, v180
	v_exp_f32_e32 v80, v80
	v_exp_f32_e32 v88, v88
	v_add_f32_e32 v80, 1.0, v80
	v_add_f32_e32 v88, 1.0, v88
	v_rcp_f32_e32 v80, v80
	v_rcp_f32_e32 v88, v88
	v_mul_f32_e32 v80, v182, v80
	v_mul_f32_e32 v88, v182, v88
	v_exp_f32_e32 v80, v80
	v_exp_f32_e32 v88, v88
	v_fma_f32 v12, -v80, v80, 1.0
	v_fma_f32 v13, -v88, v88, 1.0
	v_max_f32_e32 v12, 0, v12
	v_max_f32_e32 v13, 0, v13
	v_sqrt_f32_e32 v12, v12
	v_sqrt_f32_e32 v13, v13
	ds_write_b32 v186, v80 offset:28672
	ds_write_b32 v186, v88 offset:29184
	v_mfma_f32_32x32x16_bf16 v[16:31], v[76:79], v[232:235], v[16:31]
	v_fma_f32 v80, v14, v91, v180
	v_fma_f32 v88, v15, v91, v180
	v_exp_f32_e32 v80, v80
	v_exp_f32_e32 v88, v88
	v_add_f32_e32 v80, 1.0, v80
	v_add_f32_e32 v88, 1.0, v88
	v_rcp_f32_e32 v80, v80
	v_rcp_f32_e32 v88, v88
	v_mul_f32_e32 v80, v182, v80
	v_mul_f32_e32 v88, v182, v88
	v_exp_f32_e32 v80, v80
	v_exp_f32_e32 v88, v88
	v_fma_f32 v14, -v80, v80, 1.0
	v_fma_f32 v15, -v88, v88, 1.0
	v_max_f32_e32 v14, 0, v14
	v_max_f32_e32 v15, 0, v15
	v_sqrt_f32_e32 v14, v14
	v_sqrt_f32_e32 v15, v15
	ds_write_b32 v186, v80 offset:29696
; __device__ __forceinline__ float bf2f(u16 x) { return __uint_as_float(((unsigned)x) << 16); }
; __device__ __forceinline__ float fexp(float x) { return __builtin_amdgcn_exp2f(x * 1.4426950408889634f); }
; __device__ __forceinline__ int crow(int r, int hi) { return (r & 3) + 8 * (r >> 2) + 4 * hi; }
; template <int PASS>
; __device__ __forceinline__ void lru_tile_phase(const Params& p, int jl, int Mrows, char* smem, int tid, int bid) {
;     ...
;       const u16* xsrc = P2 + (size_t)(rowbase - sloc) * 2048 + 1024 + col;
; #pragma unroll
;       for (int i = 0; i < 19; ++i) {
;         const int s = sloc + t0 + i - 2;
;         const int sc = s < 0 ? 0 : (s >= TT ? TT - 1 : s);
;         xraw[i] = xsrc[(size_t)sc * 2048];
;       }
;     ...
; #pragma unroll
;         for (int r = 0; r < 16; ++r) {
;           const int tok = tb * 32 + crow(r, hi);
;           const float xc = bf2f(*(const u16*)(xcL + swz256(tok, chl >> 3) + (chl & 7) * 2));
;           const float la = c_sp * __builtin_amdgcn_rcpf(1.f + fexp(-(acc0[r] + c_ba)));
;           const float ii = __builtin_amdgcn_rcpf(1.f + fexp(-(acc1[r] + c_bx)));
;           const float av = fexp(la);
;           aL[(dh * 64 + tok) * 128 + chl] = av;
;           uL[(dh * 64 + tok) * 128 + chl] = __builtin_amdgcn_sqrtf(fmaxf(1.f - av * av, 0.f)) * (ii * xc);
;         }
;       }
;     }
;     __syncthreads();
	ds_write_b32 v186, v88 offset:30208
	v_fma_f32 v81, v16, v91, v181
	v_fma_f32 v89, v17, v91, v181
	v_exp_f32_e32 v81, v81
	v_exp_f32_e32 v89, v89
	v_add_f32_e32 v81, 1.0, v81
	v_add_f32_e32 v89, 1.0, v89
	v_rcp_f32_e32 v81, v81
	v_rcp_f32_e32 v89, v89
	v_mul_f32_e32 v81, v81, v32
	v_mul_f32_e32 v89, v89, v33
	v_mul_f32_e32 v81, v0, v81
	v_mul_f32_e32 v89, v1, v89
	ds_write_b32 v187, v81 offset:16384
	ds_write_b32 v187, v89 offset:16896
	v_fma_f32 v81, v18, v91, v181
	v_fma_f32 v89, v19, v91, v181
	v_exp_f32_e32 v81, v81
	v_exp_f32_e32 v89, v89
	v_add_f32_e32 v81, 1.0, v81
	v_add_f32_e32 v89, 1.0, v89
	v_rcp_f32_e32 v81, v81
	v_rcp_f32_e32 v89, v89
	v_mul_f32_e32 v81, v81, v34
	v_mul_f32_e32 v89, v89, v35
	v_mul_f32_e32 v81, v2, v81
	v_mul_f32_e32 v89, v3, v89
	ds_write_b32 v187, v81 offset:17408
	ds_write_b32 v187, v89 offset:17920
	v_fma_f32 v81, v20, v91, v181
	v_fma_f32 v89, v21, v91, v181
	v_exp_f32_e32 v81, v81
	v_exp_f32_e32 v89, v89
	v_add_f32_e32 v81, 1.0, v81
	v_add_f32_e32 v89, 1.0, v89
	v_rcp_f32_e32 v81, v81
	v_rcp_f32_e32 v89, v89
	v_mul_f32_e32 v81, v81, v36
	v_mul_f32_e32 v89, v89, v37
	v_mul_f32_e32 v81, v4, v81
	v_mul_f32_e32 v89, v5, v89
	ds_write_b32 v187, v81 offset:20480
	ds_write_b32 v187, v89 offset:20992
	v_fma_f32 v81, v22, v91, v181
	v_fma_f32 v89, v23, v91, v181
	v_exp_f32_e32 v81, v81
	v_exp_f32_e32 v89, v89
	v_add_f32_e32 v81, 1.0, v81
	v_add_f32_e32 v89, 1.0, v89
	v_rcp_f32_e32 v81, v81
	v_rcp_f32_e32 v89, v89
	v_mul_f32_e32 v81, v81, v38
	v_mul_f32_e32 v89, v89, v39
	v_mul_f32_e32 v81, v6, v81
	v_mul_f32_e32 v89, v7, v89
	ds_write_b32 v187, v81 offset:21504
	ds_write_b32 v187, v89 offset:22016
	v_fma_f32 v81, v24, v91, v181
	v_fma_f32 v89, v25, v91, v181
	v_exp_f32_e32 v81, v81
	v_exp_f32_e32 v89, v89
	v_add_f32_e32 v81, 1.0, v81
	v_add_f32_e32 v89, 1.0, v89
	v_rcp_f32_e32 v81, v81
	v_rcp_f32_e32 v89, v89
	v_mul_f32_e32 v81, v81, v40
	v_mul_f32_e32 v89, v89, v41
	v_mul_f32_e32 v81, v8, v81
	v_mul_f32_e32 v89, v9, v89
	ds_write_b32 v187, v81 offset:24576
	ds_write_b32 v187, v89 offset:25088
	v_fma_f32 v81, v26, v91, v181
	v_fma_f32 v89, v27, v91, v181
	v_exp_f32_e32 v81, v81
	v_exp_f32_e32 v89, v89
	v_add_f32_e32 v81, 1.0, v81
	v_add_f32_e32 v89, 1.0, v89
	v_rcp_f32_e32 v81, v81
	v_rcp_f32_e32 v89, v89
	v_mul_f32_e32 v81, v81, v42
	v_mul_f32_e32 v89, v89, v43
	v_mul_f32_e32 v81, v10, v81
	v_mul_f32_e32 v89, v11, v89
	ds_write_b32 v187, v81 offset:25600
	ds_write_b32 v187, v89 offset:26112
	v_fma_f32 v81, v28, v91, v181
	v_fma_f32 v89, v29, v91, v181
	v_exp_f32_e32 v81, v81
	v_exp_f32_e32 v89, v89
	v_add_f32_e32 v81, 1.0, v81
	v_add_f32_e32 v89, 1.0, v89
	v_rcp_f32_e32 v81, v81
	v_rcp_f32_e32 v89, v89
	v_mul_f32_e32 v81, v81, v44
	v_mul_f32_e32 v89, v89, v45
	v_mul_f32_e32 v81, v12, v81
	v_mul_f32_e32 v89, v13, v89
	ds_write_b32 v187, v81 offset:28672
	ds_write_b32 v187, v89 offset:29184
	v_fma_f32 v81, v30, v91, v181
	v_fma_f32 v89, v31, v91, v181
	v_exp_f32_e32 v81, v81
	v_exp_f32_e32 v89, v89
	v_add_f32_e32 v81, 1.0, v81
	v_add_f32_e32 v89, 1.0, v89
	v_rcp_f32_e32 v81, v81
	v_rcp_f32_e32 v89, v89
	v_mul_f32_e32 v81, v81, v46
	v_mul_f32_e32 v89, v89, v47
	v_mul_f32_e32 v81, v14, v81
	v_mul_f32_e32 v89, v15, v89
	ds_write_b32 v187, v81 offset:29696
	ds_write_b32 v187, v89 offset:30208
	s_waitcnt lgkmcnt(0)
	s_barrier
	s_add_u32 s0, s6, s71
	s_cmp_lt_u32 s0, 0x1100
	s_cbranch_scc0 .Llru2_nopf
	s_lshr_b32 s10, s0, 3
	s_and_b32 s11, s0, 7
	s_movk_i32 s0, 0x1000
	s_cmp_lt_u32 s10, 512
	s_cselect_b32 s4, 0, 512
	s_cselect_b32 s5, 0, 0x8000
	s_cselect_b32 s1, 63, 3
	s_cselect_b32 s21, s0, 0x100
	s_sub_u32 s0, s10, s4
	s_lshl_b32 s20, s0, 6
	s_add_u32 s20, s20, s5
	s_and_b32 s10, s0, s1
	s_lshl_b32 s10, s10, 6
	s_cmp_eq_u32 s10, 0
	s_cselect_b32 s4, 0, -2
	s_add_u32 s0, s10, 64
	s_cmp_eq_u32 s0, s21
	s_cselect_b32 s5, 63, 0x41
	s_lshl_b32 s0, s20, 12
	s_lshl_b32 s1, s11, 8
	s_add_u32 s0, s0, s1
	s_add_u32 s0, s92, s0
	s_addc_u32 s1, s93, 0
	s_sub_u32 s0, s0, 0x1800
	s_subb_u32 s1, s1, 0
	v_add_u32_e32 v44, -2, v190
	v_max_i32_e32 v49, s4, v44
	v_min_i32_e32 v49, s5, v49
	v_add_u32_e32 v195, 2, v49
	v_lshl_add_u32 v195, v195, 12, v191
	global_load_dwordx4 v[56:59], v195, s[0:1]
	v_add_u32_e32 v45, -1, v190
	v_max_i32_e32 v50, s4, v45
	v_min_i32_e32 v50, s5, v50
	v_add_u32_e32 v195, 2, v50
	v_lshl_add_u32 v195, v195, 12, v191
	global_load_dwordx4 v[60:63], v195, s[0:1]
	v_add_u32_e32 v46, 0, v190
	v_max_i32_e32 v51, s4, v46
	v_min_i32_e32 v51, s5, v51
	v_add_u32_e32 v195, 2, v51
	v_lshl_add_u32 v195, v195, 12, v191
	global_load_dwordx4 v[64:67], v195, s[0:1]
	v_add_u32_e32 v47, 1, v190
	v_max_i32_e32 v52, s4, v47
	v_min_i32_e32 v52, s5, v52
	v_add_u32_e32 v195, 2, v52
	v_lshl_add_u32 v195, v195, 12, v191
	global_load_dwordx4 v[68:71], v195, s[0:1]
	v_add_u32_e32 v48, 2, v190
	v_max_i32_e32 v53, s4, v48
	v_min_i32_e32 v53, s5, v53
	v_add_u32_e32 v195, 2, v53
	v_lshl_add_u32 v195, v195, 12, v191
	global_load_dwordx4 v[72:75], v195, s[0:1]
	s_mov_b32 s10, 1
	s_branch .Llru2_pfdone

; __device__ __forceinline__ u16 f2bf(float x) { return (u16)(cvtpk(x, 0.f) & 0xffffu); }
; __device__ __forceinline__ float fexp(float x) { return __builtin_amdgcn_exp2f(x * 1.4426950408889634f); }
; __device__ __forceinline__ float flog(float x) { return __builtin_amdgcn_logf(x) * 0.6931471805599453f; }
; template <int PASS>
; __device__ __forceinline__ void lru_tile_phase(const Params& p, int jl, int Mrows, char* smem, int tid, int bid) {
;     ...
; #pragma unroll
;       for (int i = 0; i < 19; ++i) {
;         const int s = sloc + t0 + i - 2;
;         xb[i] = (s >= 0 && s < TT) ? __uint_as_float(xraw[i] << 16) : 0.f;
;       }
; #pragma unroll
;       for (int i = 0; i < 16; ++i) {
;         const float xc = cb + cw0 * xb[i] + cw1 * xb[i + 1] + cw2 * xb[i + 2] + cw3 * xb[i + 3];
;         *(u16*)(xcL + swz256(t0 + i, ch >> 3) + (ch & 7) * 2) = f2bf(xc);
;       }
;     }
;     __syncthreads();
;     {
;       const int cbk = wid & 3, dh = wid >> 2;
;       const int chl = cbk * 32 + l32, col = n * 128 + chl;
;       if (n != n_loaded) {
;         const u16* wbase = Wbd + (size_t)n * 16384 + (size_t)chl * 128 + hi * 8;
; #pragma unroll
;         for (int k16 = 0; k16 < 8; ++k16) {
;           wb0[k16] = *(const bf16x8*)(wbase + (size_t)(dh * 2 + 0) * 131072 + k16 * 16);
;           wb1[k16] = *(const bf16x8*)(wbase + (size_t)(dh * 2 + 1) * 131072 + k16 * 16);
;         }
;         const float* pba = dh ? p.in[26] : p.in[21]; const float* pbx = dh ? p.in[28] : p.in[23]; const float* plam = dh ? p.in[29] : p.in[24];
;         c_ba = pba[(size_t)jl * 1024 + col]; c_bx = pbx[(size_t)jl * 1024 + col];
;         c_sp = -8.f * flog(1.f + fexp(-plam[(size_t)jl * 1024 + col]));
;         n_loaded = n;
;       }
; #pragma unroll
;       for (int tb = 0; tb < 2; ++tb) {
;         f32x16 acc0, acc1;
; #pragma unroll
;         for (int r = 0; r < 16; ++r) { acc0[r] = 0.f; acc1[r] = 0.f; }
;         bf16x8 af[8];
; #pragma unroll
;         for (int k16 = 0; k16 < 8; ++k16) af[k16] = *(const bf16x8*)(xcL + swz256(tb * 32 + l32, k16 * 2 + hi));
; #pragma unroll
;         for (int k16 = 0; k16 < 8; ++k16) {
;           acc0 = __builtin_amdgcn_mfma_f32_32x32x16_bf16(af[k16], wb0[k16], acc0, 0, 0, 0);
;           acc1 = __builtin_amdgcn_mfma_f32_32x32x16_bf16(af[k16], wb1[k16], acc1, 0, 0, 0);
;         }
.Llru1_cv4b:
	v_cmp_eq_u32_e32 vcc, v48, v53
	s_nop 1
	v_cndmask_b32_e32 v72, 0, v72, vcc
	v_cndmask_b32_e32 v73, 0, v73, vcc
	v_cndmask_b32_e32 v74, 0, v74, vcc
	v_cndmask_b32_e32 v75, 0, v75, vcc
	v_lshlrev_b32_e32 v36, 16, v72
	v_and_b32_e32 v37, 0xffff0000, v72
	v_lshlrev_b32_e32 v38, 16, v73
	v_and_b32_e32 v39, 0xffff0000, v73
	v_lshlrev_b32_e32 v40, 16, v74
	v_and_b32_e32 v41, 0xffff0000, v74
	v_lshlrev_b32_e32 v42, 16, v75
	v_and_b32_e32 v43, 0xffff0000, v75
	v_fmac_f32_e32 v28, v124, v36
	v_fmac_f32_e32 v29, v125, v37
	v_fmac_f32_e32 v30, v126, v38
	v_fmac_f32_e32 v31, v127, v39
	v_fmac_f32_e32 v32, v128, v40
	v_fmac_f32_e32 v33, v129, v41
	v_fmac_f32_e32 v34, v130, v42
	v_fmac_f32_e32 v35, v131, v43
	v_cvt_pk_bf16_f32 v36, v20, v21
	v_cvt_pk_bf16_f32 v37, v22, v23
	v_cvt_pk_bf16_f32 v38, v24, v25
	v_cvt_pk_bf16_f32 v39, v26, v27
	v_cvt_pk_bf16_f32 v40, v28, v29
	v_cvt_pk_bf16_f32 v41, v30, v31
	v_cvt_pk_bf16_f32 v42, v32, v33
	v_cvt_pk_bf16_f32 v43, v34, v35
	ds_write_b128 v183, v[36:39]
	ds_write_b128 v184, v[40:43]
	s_waitcnt lgkmcnt(0)
	s_barrier
	ds_read_b128 v[48:51], v185 offset:0
	v_xor_b32_e32 v196, 32, v185
	ds_read_b128 v[52:55], v196 offset:0
	v_xor_b32_e32 v195, 64, v185
	ds_read_b128 v[56:59], v195 offset:0
	v_xor_b32_e32 v196, 96, v185
	ds_read_b128 v[60:63], v196 offset:0
	v_xor_b32_e32 v195, 128, v185
	ds_read_b128 v[64:67], v195 offset:0
	v_xor_b32_e32 v196, 160, v185
	ds_read_b128 v[68:71], v196 offset:0
	v_xor_b32_e32 v195, 192, v185
	ds_read_b128 v[72:75], v195 offset:0
	v_xor_b32_e32 v196, 224, v185
	ds_read_b128 v[76:79], v196 offset:0
	s_waitcnt lgkmcnt(7)
	v_mfma_f32_32x32x16_bf16 v[0:15], v[48:51], v[140:143], 0
	s_waitcnt lgkmcnt(6)
	v_mfma_f32_32x32x16_bf16 v[0:15], v[52:55], v[144:147], v[0:15]
	s_waitcnt lgkmcnt(5)
	v_mfma_f32_32x32x16_bf16 v[0:15], v[56:59], v[148:151], v[0:15]
	s_waitcnt lgkmcnt(4)
	v_mfma_f32_32x32x16_bf16 v[0:15], v[60:63], v[152:155], v[0:15]
	s_waitcnt lgkmcnt(3)
	v_mfma_f32_32x32x16_bf16 v[0:15], v[64:67], v[156:159], v[0:15]
	s_waitcnt lgkmcnt(2)
	v_mfma_f32_32x32x16_bf16 v[0:15], v[68:71], v[160:163], v[0:15]
	s_waitcnt lgkmcnt(1)
	v_mfma_f32_32x32x16_bf16 v[0:15], v[72:75], v[164:167], v[0:15]
	s_waitcnt lgkmcnt(0)
	v_mfma_f32_32x32x16_bf16 v[0:15], v[76:79], v[168:171], v[0:15]
	s_and_b32 s0, s27, 3
	s_cmp_eq_u32 s0, 0
	s_cbranch_scc0 .Llru1_id0_0
	v_mfma_f32_32x32x16_bf16 v[32:47], v[48:51], v[172:175], 0
	v_mfma_f32_32x32x16_bf16 v[32:47], v[52:55], v[176:179], v[32:47]

; __device__ __forceinline__ unsigned xb_ld(unsigned* p) { return __hip_atomic_load(p, __ATOMIC_RELAXED, __HIP_MEMORY_SCOPE_AGENT); }
; __device__ __forceinline__ unsigned xb_add(unsigned* p, unsigned v) { return __hip_atomic_fetch_add(p, v, __ATOMIC_RELAXED, __HIP_MEMORY_SCOPE_AGENT); }
; __device__ __forceinline__ void grid_barrier(unsigned* bar, volatile unsigned* st) {
;     ...
;       else { while (xb_ld(&bar[XB_TOPGEN]) == tg) __builtin_amdgcn_s_sleep(1); }
;       __builtin_amdgcn_fence(__ATOMIC_ACQUIRE, "agent");
;       xb_add(&bar[XB_XGEN(x)], 1u);
;       asm volatile("s_waitcnt vmcnt(0)" ::: "memory");
;     } else {
;       while (xb_ld(&bar[XB_XGEN(x)]) == gen) __builtin_amdgcn_s_sleep(1);
.LBB0_885:
	s_nop 0
	global_load_dword v3, v[0:1], off sc1
	s_waitcnt vmcnt(0)
	v_cmp_ne_u32_e32 vcc, v3, v2
	s_or_b64 s[10:11], vcc, s[10:11]
	s_andn2_b64 exec, exec, s[10:11]
	s_cbranch_execnz .LBB0_885

; __device__ __forceinline__ unsigned xb_ld(unsigned* p) { return __hip_atomic_load(p, __ATOMIC_RELAXED, __HIP_MEMORY_SCOPE_AGENT); }
; __device__ __forceinline__ void grid_barrier(unsigned* bar, volatile unsigned* st) {
;     ...
;       else { while (xb_ld(&bar[XB_TOPGEN]) == tg) __builtin_amdgcn_s_sleep(1); }
.LBB0_893:
	s_nop 0
	global_load_dword v0, v201, s[20:21] sc1
	s_waitcnt vmcnt(0)
	v_cmp_ne_u32_e32 vcc, v0, v1
	s_or_b64 s[10:11], vcc, s[10:11]
	s_andn2_b64 exec, exec, s[10:11]
	s_cbranch_execnz .LBB0_893
